# v46 + sample-attention Q rows 3/4 and sink load issued with rows 1/2 (counted vmcnt 4/3/2/1/0)
# speedup vs baseline: 1.0044x; 1.0044x over previous
.LBB0_597:
	s_or_b64 exec, exec, s[0:1]
	s_ashr_i32 s0, s20, 6
	s_cmp_lt_i32 s0, 2
	s_waitcnt lgkmcnt(0)
	s_barrier
	s_cbranch_scc0 .LBB0_599
	v_bfe_u32 v0, v84, 3, 2
	v_lshl_or_b32 v0, s0, 2, v0
	v_readlane_b32 s0, v255, 8
	v_mov_b64_e32 v[2:3], s[68:69]
	v_bfe_u32 v116, v84, 5, 1
	v_add_u32_e32 v80, s0, v0
	v_readlane_b32 s0, v255, 10
	v_lshlrev_b32_e32 v4, 6, v80
	v_ashrrev_i32_e32 v5, 31, v4
	v_or_b32_e32 v0, s0, v66
	s_movk_i32 s0, 0x3400
	v_mad_u64_u32 v[2:3], s[0:1], v0, s0, v[2:3]
	v_lshlrev_b64 v[82:83], 1, v[4:5]
	v_lshrrev_b32_e32 v4, 1, v84
	v_lshl_add_u64 v[2:3], v[2:3], 0, v[82:83]
	v_and_b32_e32 v4, 16, v4
	v_mov_b32_e32 v5, v1
	v_lshl_add_u64 v[104:105], v[2:3], 0, v[4:5]
	global_load_dwordx4 v[68:71], v[104:105], off
	global_load_dwordx4 v[88:91], v[104:105], off offset:32
	global_load_dwordx4 v[100:103], v[104:105], off offset:64
	global_load_dwordx4 v[244:247], v[104:105], off offset:96
	v_ashrrev_i32_e32 v249, 31, v80
	v_mov_b32_e32 v248, v80
	v_lshl_add_u64 v[250:251], v[248:249], 2, s[12:13]
	global_load_dword v85, v[250:251], off
	v_and_b32_e32 v86, 31, v84
	v_lshl_add_u32 v117, v116, 4, 0
	v_mad_u32_u24 v67, v86, s52, v117
	ds_read_b128 v[2:5], v67
	ds_read_b128 v[72:75], v67 offset:32
	v_and_b32_e32 v6, 63, v84
	v_or_b32_e32 v87, 32, v6
	v_mad_u32_u24 v81, v87, s52, v117
	v_or_b32_e32 v6, 0x60, v6
	v_mad_u32_u24 v108, v6, s52, v117
	v_or_b32_e32 v118, 0x80, v66
	s_waitcnt vmcnt(4) lgkmcnt(1)
	v_mfma_f32_32x32x16_bf16 v[50:65], v[2:5], v[68:71], 0
	ds_read_b128 v[2:5], v81
	ds_read_b128 v[76:79], v81 offset:32
	ds_read_b128 v[92:95], v67 offset:9248
	s_waitcnt lgkmcnt(2)
	v_mfma_f32_32x32x16_bf16 v[34:49], v[2:5], v[68:71], 0
	ds_read_b128 v[2:5], v67 offset:9216
	s_waitcnt lgkmcnt(0)
	v_mfma_f32_32x32x16_bf16 v[18:33], v[2:5], v[68:71], 0
	ds_read_b128 v[2:5], v108
	ds_read_b128 v[96:99], v108 offset:32
	s_waitcnt lgkmcnt(1)
	v_mfma_f32_32x32x16_bf16 v[2:17], v[2:5], v[68:71], 0
	s_waitcnt vmcnt(3)
	v_mfma_f32_32x32x16_bf16 v[50:65], v[72:75], v[88:91], v[50:65]
	v_mfma_f32_32x32x16_bf16 v[34:49], v[76:79], v[88:91], v[34:49]
	v_mfma_f32_32x32x16_bf16 v[18:33], v[92:95], v[88:91], v[18:33]
	ds_read_b128 v[72:75], v67 offset:64
	ds_read_b128 v[76:79], v67 offset:96
	s_waitcnt lgkmcnt(2)
	v_mfma_f32_32x32x16_bf16 v[2:17], v[96:99], v[88:91], v[2:17]
	s_waitcnt vmcnt(2) lgkmcnt(1)
	v_mfma_f32_32x32x16_bf16 v[50:65], v[72:75], v[100:103], v[50:65]
	ds_read_b128 v[72:75], v81 offset:64
	ds_read_b128 v[96:99], v81 offset:96
	s_waitcnt lgkmcnt(1)
	v_mfma_f32_32x32x16_bf16 v[34:49], v[72:75], v[100:103], v[34:49]
	ds_read_b128 v[72:75], v67 offset:9280
	ds_read_b128 v[104:107], v67 offset:9312
	s_waitcnt lgkmcnt(1)
	v_mfma_f32_32x32x16_bf16 v[18:33], v[72:75], v[100:103], v[18:33]
	ds_read_b128 v[72:75], v108 offset:64
	v_lshlrev_b32_e32 v80, 2, v116
	v_cmp_gt_u32_e32 vcc, v80, v66
	v_or_b32_e32 v81, 2, v80
	v_or_b32_e32 v120, 3, v80
	s_waitcnt vmcnt(1)
	v_mfma_f32_32x32x16_bf16 v[50:65], v[76:79], v[244:247], v[50:65]
	v_cmp_gt_u32_e64 s[4:5], v81, v66
	v_or_b32_e32 v121, 0x82, v80
	v_or_b32_e32 v122, 0x83, v80
	v_cmp_lt_u32_e64 s[0:1], v80, v66
	s_nop 7
	v_cndmask_b32_e32 v123, v215, v50, vcc
	s_waitcnt lgkmcnt(0)
	v_mfma_f32_32x32x16_bf16 v[2:17], v[72:75], v[100:103], v[2:17]
	v_max_f32_e32 v50, v123, v123
	v_cndmask_b32_e64 v125, v215, v52, s[4:5]
	v_cmp_gt_u32_e64 s[4:5], v120, v66
	v_cndmask_b32_e64 v124, v51, v215, s[0:1]
	s_nop 0
	v_cndmask_b32_e64 v120, v215, v53, s[4:5]
	v_lshlrev_b64 v[52:53], 13, v[0:1]
	v_mfma_f32_32x32x16_bf16 v[34:49], v[96:99], v[244:247], v[34:49]
	v_mfma_f32_32x32x16_bf16 v[18:33], v[104:107], v[244:247], v[18:33]
	ds_read_b128 v[76:79], v108 offset:96
	ds_read_b128 v[96:99], v67 offset:18432
	ds_read_b128 v[104:107], v67 offset:18464
	ds_read_b128 v[108:111], v67 offset:18496
	ds_read_b128 v[112:115], v67 offset:18528
	s_waitcnt vmcnt(0)
	v_max_f32_e32 v67, v85, v85
	v_max_f32_e32 v50, v67, v50
	s_waitcnt lgkmcnt(4)
	v_mfma_f32_32x32x16_bf16 v[2:17], v[76:79], v[244:247], v[2:17]
	v_max3_f32 v50, v50, v124, v125
	v_max3_f32 v50, v50, v120, v54
	v_max3_f32 v50, v50, v55, v56
	v_max3_f32 v50, v50, v57, v58
	v_max3_f32 v50, v50, v59, v60
	v_max3_f32 v50, v50, v61, v62
	v_max3_f32 v50, v50, v63, v64
	s_waitcnt lgkmcnt(3)
	v_mfma_f32_32x32x16_bf16 v[66:81], v[96:99], v[68:71], 0
	v_max3_f32 v50, v50, v65, v34
	v_max3_f32 v50, v50, v35, v36
	v_max3_f32 v50, v50, v37, v38
	v_max3_f32 v50, v50, v39, v40
	v_max3_f32 v50, v50, v41, v42
	v_max3_f32 v50, v50, v43, v44
	v_max3_f32 v50, v50, v45, v46
	s_waitcnt lgkmcnt(2)
	v_mfma_f32_32x32x16_bf16 v[66:81], v[104:107], v[88:91], v[66:81]
	v_max3_f32 v50, v50, v47, v48
	v_max3_f32 v50, v50, v49, v18
	v_max3_f32 v50, v50, v19, v20
	v_max3_f32 v50, v50, v21, v22
	v_max3_f32 v50, v50, v23, v24
	v_max3_f32 v50, v50, v25, v26
	v_max3_f32 v50, v50, v27, v28
	s_waitcnt lgkmcnt(1)
	v_mfma_f32_32x32x16_bf16 v[66:81], v[108:111], v[100:103], v[66:81]
	v_max3_f32 v50, v50, v29, v30
	v_max3_f32 v50, v50, v31, v32
	v_max3_f32 v50, v50, v33, v2
	v_max3_f32 v50, v50, v3, v4
	v_max3_f32 v50, v50, v5, v6
	v_max3_f32 v50, v50, v7, v8
	v_max3_f32 v50, v50, v9, v10
	s_waitcnt lgkmcnt(0)
	v_mfma_f32_32x32x16_bf16 v[66:81], v[112:115], v[244:247], v[66:81]
	v_max3_f32 v50, v50, v11, v12
	v_max3_f32 v50, v50, v13, v14
	v_max3_f32 v50, v50, v15, v16
	s_nop 8
	v_cndmask_b32_e32 v70, v66, v215, vcc
	v_cmp_le_u32_e32 vcc, v121, v118
	v_max3_f32 v50, v50, v17, v70
	v_cndmask_b32_e64 v67, v215, v67, s[0:1]
	v_cndmask_b32_e32 v66, v215, v68, vcc
	v_cmp_le_u32_e32 vcc, v122, v118
	v_max3_f32 v50, v50, v67, v66
	s_mov_b32 s0, 0xff800000
	v_cndmask_b32_e32 v51, v215, v69, vcc
	v_max3_f32 v68, v50, v51, s0
	ds_bpermute_b32 v69, v152, v68
	v_lshlrev_b32_e32 v50, 3, v116
	v_sub_u32_e32 v71, v117, v50
	s_movk_i32 s0, 0x210
	s_waitcnt lgkmcnt(0)
	v_max_f32_e32 v0, v69, v69
	v_max_f32_e32 v0, v68, v0
	v_sub_f32_e32 v68, v123, v0
	v_sub_f32_e32 v69, v124, v0
	v_mul_f32_e32 v68, 0x3fb8aa3b, v68
	v_sub_f32_e32 v72, v125, v0
	v_mul_f32_e32 v69, 0x3fb8aa3b, v69
	v_exp_f32_e32 v68, v68
	v_sub_f32_e32 v73, v120, v0
	v_mul_f32_e32 v72, 0x3fb8aa3b, v72
	v_exp_f32_e32 v69, v69
	v_sub_f32_e32 v54, v54, v0
	v_mul_f32_e32 v73, 0x3fb8aa3b, v73
	v_exp_f32_e32 v72, v72
	v_sub_f32_e32 v55, v55, v0
	v_mul_f32_e32 v54, 0x3fb8aa3b, v54
	v_exp_f32_e32 v73, v73
	v_sub_f32_e32 v56, v56, v0
	v_mul_f32_e32 v55, 0x3fb8aa3b, v55
	v_exp_f32_e32 v54, v54
	v_add_f32_e32 v74, 0, v68
	v_sub_f32_e32 v57, v57, v0
	v_mul_f32_e32 v56, 0x3fb8aa3b, v56
	v_exp_f32_e32 v55, v55
	v_add_f32_e32 v74, v69, v74
	v_sub_f32_e32 v58, v58, v0
	v_mul_f32_e32 v57, 0x3fb8aa3b, v57
	v_exp_f32_e32 v56, v56
	v_add_f32_e32 v74, v72, v74
	v_sub_f32_e32 v59, v59, v0
	v_mul_f32_e32 v58, 0x3fb8aa3b, v58
	v_exp_f32_e32 v57, v57
	v_add_f32_e32 v74, v73, v74
	v_sub_f32_e32 v60, v60, v0
	v_mul_f32_e32 v59, 0x3fb8aa3b, v59
	v_exp_f32_e32 v58, v58
	v_add_f32_e32 v74, v54, v74
	v_sub_f32_e32 v61, v61, v0
	v_mul_f32_e32 v60, 0x3fb8aa3b, v60
	v_exp_f32_e32 v59, v59
	v_add_f32_e32 v74, v55, v74
	v_mul_f32_e32 v61, 0x3fb8aa3b, v61
	v_exp_f32_e32 v60, v60
	v_add_f32_e32 v74, v56, v74
	v_sub_f32_e32 v62, v62, v0
	v_exp_f32_e32 v61, v61
	v_add_f32_e32 v74, v57, v74
	v_mul_f32_e32 v62, 0x3fb8aa3b, v62
	v_sub_f32_e32 v63, v63, v0
	v_add_f32_e32 v74, v58, v74
	v_exp_f32_e32 v62, v62
	v_mul_f32_e32 v63, 0x3fb8aa3b, v63
	v_sub_f32_e32 v64, v64, v0
	v_sub_f32_e32 v34, v34, v0
	v_add_f32_e32 v74, v59, v74
	v_exp_f32_e32 v63, v63
	v_mul_f32_e32 v64, 0x3fb8aa3b, v64
	v_sub_f32_e32 v65, v65, v0
	v_mul_f32_e32 v34, 0x3fb8aa3b, v34
	v_add_f32_e32 v74, v60, v74
	v_exp_f32_e32 v64, v64
	v_mul_f32_e32 v65, 0x3fb8aa3b, v65
	v_exp_f32_e32 v75, v34
	v_sub_f32_e32 v34, v35, v0
	v_add_f32_e32 v74, v61, v74
	v_exp_f32_e32 v65, v65
	v_mul_f32_e32 v34, 0x3fb8aa3b, v34
	v_add_f32_e32 v74, v62, v74
	v_exp_f32_e32 v76, v34
	v_sub_f32_e32 v34, v36, v0
	v_add_f32_e32 v74, v63, v74
	v_mul_f32_e32 v34, 0x3fb8aa3b, v34
	v_add_f32_e32 v74, v64, v74
	v_exp_f32_e32 v77, v34
	v_sub_f32_e32 v34, v37, v0
	v_sub_f32_e32 v35, v38, v0
	v_add_f32_e32 v74, v65, v74
	v_mul_f32_e32 v34, 0x3fb8aa3b, v34
	v_mul_f32_e32 v35, 0x3fb8aa3b, v35
	v_exp_f32_e32 v78, v34
	v_add_f32_e32 v34, v75, v74
	v_exp_f32_e32 v74, v35
	v_sub_f32_e32 v35, v39, v0
	v_mul_f32_e32 v35, 0x3fb8aa3b, v35
	v_exp_f32_e32 v79, v35
	v_sub_f32_e32 v35, v40, v0
	v_mul_f32_e32 v35, 0x3fb8aa3b, v35
	v_exp_f32_e32 v80, v35
	v_sub_f32_e32 v35, v41, v0
	v_mul_f32_e32 v35, 0x3fb8aa3b, v35
	v_exp_f32_e32 v81, v35
	v_sub_f32_e32 v35, v42, v0
	v_mul_f32_e32 v35, 0x3fb8aa3b, v35
	v_exp_f32_e32 v88, v35
	v_sub_f32_e32 v35, v43, v0
	v_mul_f32_e32 v35, 0x3fb8aa3b, v35
	v_exp_f32_e32 v89, v35
	v_sub_f32_e32 v35, v44, v0
	v_mul_f32_e32 v35, 0x3fb8aa3b, v35
	v_add_f32_e32 v34, v76, v34
	v_exp_f32_e32 v90, v35
	v_sub_f32_e32 v35, v45, v0
	v_sub_f32_e32 v18, v18, v0
	v_add_f32_e32 v34, v77, v34
	v_mul_f32_e32 v35, 0x3fb8aa3b, v35
	v_mul_f32_e32 v18, 0x3fb8aa3b, v18
	v_add_f32_e32 v34, v78, v34
	v_exp_f32_e32 v91, v35
	v_sub_f32_e32 v35, v46, v0
	v_exp_f32_e32 v96, v18
	v_sub_f32_e32 v18, v19, v0
	v_sub_f32_e32 v19, v22, v0
	v_add_f32_e32 v34, v74, v34
	v_mul_f32_e32 v35, 0x3fb8aa3b, v35
	v_mul_f32_e32 v19, 0x3fb8aa3b, v19
	v_add_f32_e32 v34, v79, v34
	v_exp_f32_e32 v92, v35
	v_sub_f32_e32 v35, v47, v0
	v_exp_f32_e32 v100, v19
	v_sub_f32_e32 v19, v23, v0
	v_add_f32_e32 v34, v80, v34
	v_mul_f32_e32 v35, 0x3fb8aa3b, v35
	v_mul_f32_e32 v19, 0x3fb8aa3b, v19
	v_add_f32_e32 v34, v81, v34
	v_exp_f32_e32 v93, v35
	v_sub_f32_e32 v35, v48, v0
	v_exp_f32_e32 v101, v19
	v_sub_f32_e32 v19, v24, v0
	v_add_f32_e32 v34, v88, v34
	v_mul_f32_e32 v35, 0x3fb8aa3b, v35
	v_mul_f32_e32 v19, 0x3fb8aa3b, v19
	v_add_f32_e32 v34, v89, v34
	v_exp_f32_e32 v94, v35
	v_sub_f32_e32 v35, v49, v0
	v_exp_f32_e32 v102, v19
	v_sub_f32_e32 v19, v25, v0
	v_add_f32_e32 v34, v90, v34
	v_mul_f32_e32 v35, 0x3fb8aa3b, v35
	v_mul_f32_e32 v18, 0x3fb8aa3b, v18
	v_mul_f32_e32 v19, 0x3fb8aa3b, v19
	v_add_f32_e32 v34, v91, v34
	v_exp_f32_e32 v95, v35
	v_exp_f32_e32 v97, v18
	v_sub_f32_e32 v18, v20, v0
	v_exp_f32_e32 v103, v19
	v_sub_f32_e32 v19, v26, v0
	v_add_f32_e32 v34, v92, v34
	v_mul_f32_e32 v18, 0x3fb8aa3b, v18
	v_mul_f32_e32 v19, 0x3fb8aa3b, v19
	v_add_f32_e32 v34, v93, v34
	v_exp_f32_e32 v98, v18
	v_sub_f32_e32 v18, v21, v0
	v_exp_f32_e32 v104, v19
	v_sub_f32_e32 v19, v27, v0
	v_add_f32_e32 v34, v94, v34
	v_mul_f32_e32 v18, 0x3fb8aa3b, v18
	v_mul_f32_e32 v19, 0x3fb8aa3b, v19
	v_add_f32_e32 v34, v95, v34
	v_exp_f32_e32 v99, v18
	v_exp_f32_e32 v105, v19
	v_sub_f32_e32 v19, v28, v0
	v_add_f32_e32 v18, v96, v34
	v_mul_f32_e32 v19, 0x3fb8aa3b, v19
	v_add_f32_e32 v18, v97, v18
	v_exp_f32_e32 v106, v19
	v_sub_f32_e32 v19, v29, v0
	v_add_f32_e32 v18, v98, v18
	v_mul_f32_e32 v19, 0x3fb8aa3b, v19
	v_add_f32_e32 v18, v99, v18
	v_exp_f32_e32 v107, v19
	v_sub_f32_e32 v19, v30, v0
	v_add_f32_e32 v18, v100, v18
	v_mul_f32_e32 v19, 0x3fb8aa3b, v19
	v_add_f32_e32 v18, v101, v18
	v_exp_f32_e32 v108, v19
	v_sub_f32_e32 v19, v31, v0
	v_add_f32_e32 v18, v102, v18
	v_mul_f32_e32 v19, 0x3fb8aa3b, v19
	v_add_f32_e32 v18, v103, v18
	v_exp_f32_e32 v109, v19
	v_sub_f32_e32 v19, v32, v0
	v_sub_f32_e32 v2, v2, v0
	v_add_f32_e32 v18, v104, v18
	v_mul_f32_e32 v19, 0x3fb8aa3b, v19
	v_mul_f32_e32 v2, 0x3fb8aa3b, v2
	v_add_f32_e32 v18, v105, v18
	v_exp_f32_e32 v110, v19
	v_sub_f32_e32 v19, v33, v0
	v_exp_f32_e32 v112, v2
	v_sub_f32_e32 v2, v3, v0
	v_add_f32_e32 v18, v106, v18
	v_mul_f32_e32 v19, 0x3fb8aa3b, v19
	v_mul_f32_e32 v2, 0x3fb8aa3b, v2
	v_add_f32_e32 v18, v107, v18
	v_exp_f32_e32 v111, v19
	v_exp_f32_e32 v113, v2
	v_sub_f32_e32 v2, v4, v0
	v_add_f32_e32 v18, v108, v18
	v_mul_f32_e32 v2, 0x3fb8aa3b, v2
	v_add_f32_e32 v18, v109, v18
	v_exp_f32_e32 v114, v2
	v_sub_f32_e32 v2, v5, v0
	v_add_f32_e32 v18, v110, v18
	v_mul_f32_e32 v2, 0x3fb8aa3b, v2
	v_add_f32_e32 v18, v111, v18
	v_exp_f32_e32 v115, v2
	v_add_f32_e32 v2, v112, v18
	v_add_f32_e32 v2, v113, v2
	v_add_f32_e32 v2, v114, v2
	v_add_f32_e32 v22, v115, v2
	v_sub_f32_e32 v2, v6, v0
	v_mul_f32_e32 v2, 0x3fb8aa3b, v2
	v_exp_f32_e32 v116, v2
	v_sub_f32_e32 v2, v7, v0
	v_sub_f32_e32 v7, v8, v0
	v_mul_f32_e32 v2, 0x3fb8aa3b, v2
	v_mul_f32_e32 v7, 0x3fb8aa3b, v7
	v_exp_f32_e32 v117, v2
	v_cvt_pk_bf16_f32 v2, v68, v69
	v_mad_u32_u24 v6, v86, s0, v71
	v_exp_f32_e32 v69, v7
	v_mad_u32_u24 v7, v87, s0, v71
	v_add_u32_e32 v68, 0x9000, v6
	v_add_u32_e32 v71, 0x9000, v7
	v_cvt_pk_bf16_f32 v3, v72, v73
	v_cvt_pk_bf16_f32 v4, v54, v55
	v_cvt_pk_bf16_f32 v5, v56, v57
	ds_read2_b64 v[18:21], v68 offset1:2
	v_add_f32_e32 v6, v116, v22
	ds_read2_b64 v[22:25], v71 offset1:2
	v_sub_f32_e32 v73, v9, v0
	v_add_f32_e32 v6, v117, v6
	s_waitcnt lgkmcnt(1)
	v_mfma_f32_32x32x16_bf16 v[34:49], v[18:21], v[2:5], 0
	v_add_f32_e32 v72, v69, v6
	v_cvt_pk_bf16_f32 v6, v58, v59
	v_cvt_pk_bf16_f32 v7, v60, v61
	v_cvt_pk_bf16_f32 v8, v62, v63
	v_cvt_pk_bf16_f32 v9, v64, v65
	ds_read2_b64 v[54:57], v68 offset0:4 offset1:6
	v_sub_f32_e32 v11, v11, v0
	s_waitcnt lgkmcnt(1)
	v_mfma_f32_32x32x16_bf16 v[18:33], v[22:25], v[2:5], 0
	v_mul_f32_e32 v2, 0x3fb8aa3b, v73
	v_exp_f32_e32 v62, v2
	v_sub_f32_e32 v2, v10, v0
	v_mul_f32_e32 v2, 0x3fb8aa3b, v2
	v_exp_f32_e32 v63, v2
	ds_read2_b64 v[2:5], v71 offset0:4 offset1:6
	v_add_f32_e32 v10, v62, v72
	s_waitcnt lgkmcnt(0)
	v_mfma_f32_32x32x16_bf16 v[18:33], v[2:5], v[6:9], v[18:33]
	v_mul_f32_e32 v2, 0x3fb8aa3b, v11
	v_exp_f32_e32 v64, v2
	v_sub_f32_e32 v2, v12, v0
	v_mul_f32_e32 v2, 0x3fb8aa3b, v2
	v_exp_f32_e32 v65, v2
	v_add_f32_e32 v10, v63, v10
	v_sub_f32_e32 v15, v15, v0
	v_mfma_f32_32x32x16_bf16 v[34:49], v[54:57], v[6:9], v[34:49]
	v_cvt_pk_bf16_f32 v54, v75, v76
	v_cvt_pk_bf16_f32 v55, v77, v78
	v_cvt_pk_bf16_f32 v56, v74, v79
	v_cvt_pk_bf16_f32 v57, v80, v81
	ds_read2_b64 v[58:61], v68 offset0:8 offset1:10
	ds_read2_b64 v[2:5], v71 offset0:8 offset1:10
	v_add_f32_e32 v6, v64, v10
	s_waitcnt lgkmcnt(1)
	v_mfma_f32_32x32x16_bf16 v[34:49], v[58:61], v[54:57], v[34:49]
	v_sub_f32_e32 v59, v13, v0
	v_add_f32_e32 v58, v65, v6
	v_cvt_pk_bf16_f32 v6, v88, v89
	v_cvt_pk_bf16_f32 v7, v90, v91
	v_cvt_pk_bf16_f32 v8, v92, v93
	v_cvt_pk_bf16_f32 v9, v94, v95
	ds_read2_b64 v[10:13], v68 offset0:12 offset1:14
	s_waitcnt lgkmcnt(1)
	v_mfma_f32_32x32x16_bf16 v[18:33], v[2:5], v[54:57], v[18:33]
	v_mul_f32_e32 v2, 0x3fb8aa3b, v59
	v_exp_f32_e32 v59, v2
	v_sub_f32_e32 v2, v14, v0
	v_mul_f32_e32 v2, 0x3fb8aa3b, v2
	v_exp_f32_e32 v60, v2
	ds_read2_b64 v[2:5], v71 offset0:12 offset1:14
	v_add_f32_e32 v14, v59, v58
	s_waitcnt lgkmcnt(0)
	v_mfma_f32_32x32x16_bf16 v[18:33], v[2:5], v[6:9], v[18:33]
	v_mul_f32_e32 v2, 0x3fb8aa3b, v15
	v_exp_f32_e32 v58, v2
	v_sub_f32_e32 v2, v16, v0
	v_mul_f32_e32 v2, 0x3fb8aa3b, v2
	v_exp_f32_e32 v61, v2
	v_add_f32_e32 v14, v60, v14
	v_sub_f32_e32 v51, v51, v0
	v_mfma_f32_32x32x16_bf16 v[34:49], v[10:13], v[6:9], v[34:49]
	v_cvt_pk_bf16_f32 v10, v96, v97
	v_cvt_pk_bf16_f32 v11, v98, v99
	v_cvt_pk_bf16_f32 v12, v100, v101
	v_cvt_pk_bf16_f32 v13, v102, v103
	ds_read2_b64 v[54:57], v68 offset0:16 offset1:18
	ds_read2_b64 v[2:5], v71 offset0:16 offset1:18
	v_add_f32_e32 v6, v58, v14
	s_waitcnt lgkmcnt(1)
	v_mfma_f32_32x32x16_bf16 v[34:49], v[54:57], v[10:13], v[34:49]
	v_sub_f32_e32 v55, v17, v0
	v_add_f32_e32 v54, v61, v6
	v_cvt_pk_bf16_f32 v6, v104, v105
	v_cvt_pk_bf16_f32 v7, v106, v107
	v_cvt_pk_bf16_f32 v8, v108, v109
	v_cvt_pk_bf16_f32 v9, v110, v111
	ds_read2_b64 v[14:17], v68 offset0:20 offset1:22
	s_waitcnt lgkmcnt(1)
	v_mfma_f32_32x32x16_bf16 v[18:33], v[2:5], v[10:13], v[18:33]
	v_mul_f32_e32 v2, 0x3fb8aa3b, v55
	v_exp_f32_e32 v55, v2
	v_sub_f32_e32 v2, v70, v0
	v_mul_f32_e32 v2, 0x3fb8aa3b, v2
	v_exp_f32_e32 v56, v2
	ds_read2_b64 v[2:5], v71 offset0:20 offset1:22
	v_sub_f32_e32 v57, v67, v0
	s_waitcnt lgkmcnt(0)
	v_mfma_f32_32x32x16_bf16 v[18:33], v[2:5], v[6:9], v[18:33]
	v_mul_f32_e32 v2, 0x3fb8aa3b, v57
	v_exp_f32_e32 v57, v2
	v_sub_f32_e32 v2, v66, v0
	v_add_f32_e32 v10, v55, v54
	v_mul_f32_e32 v2, 0x3fb8aa3b, v2
	v_add_f32_e32 v54, v56, v10
	v_cvt_pk_bf16_f32 v10, v112, v113
	v_cvt_pk_bf16_f32 v11, v114, v115
	v_cvt_pk_bf16_f32 v12, v116, v117
	v_cvt_pk_bf16_f32 v13, v69, v62
	v_exp_f32_e32 v62, v2
	ds_read2_b64 v[2:5], v71 offset0:24 offset1:26
	v_mfma_f32_32x32x16_bf16 v[34:49], v[14:17], v[6:9], v[34:49]
	ds_read2_b64 v[14:17], v68 offset0:24 offset1:26
	v_add_f32_e32 v6, v57, v54
	v_add_f32_e32 v54, v62, v6
	v_cvt_pk_bf16_f32 v6, v63, v64
	v_cvt_pk_bf16_f32 v7, v65, v59
	v_cvt_pk_bf16_f32 v8, v60, v58
	v_cvt_pk_bf16_f32 v9, v61, v55
	s_waitcnt lgkmcnt(1)
	v_mfma_f32_32x32x16_bf16 v[18:33], v[2:5], v[10:13], v[18:33]
	v_mul_f32_e32 v2, 0x3fb8aa3b, v51
	s_waitcnt lgkmcnt(0)
	v_mfma_f32_32x32x16_bf16 v[34:49], v[14:17], v[10:13], v[34:49]
	v_exp_f32_e32 v11, v2
	v_sub_f32_e32 v2, 0xff800000, v0
	v_mul_f32_e32 v2, 0x3fb8aa3b, v2
	v_exp_f32_e32 v51, v2
	ds_read2_b64 v[2:5], v71 offset0:28 offset1:30
	ds_read2_b64 v[14:17], v68 offset0:28 offset1:30
	v_add_f32_e32 v10, v11, v54
	v_add_f32_e32 v10, v51, v10
	v_add_f32_e32 v54, v51, v10
	s_waitcnt lgkmcnt(1)
	v_mfma_f32_32x32x16_bf16 v[18:33], v[2:5], v[6:9], v[18:33]
	v_add_f32_e32 v2, v51, v54
	v_add_f32_e32 v2, v51, v2
	v_add_f32_e32 v2, v51, v2
	v_add_f32_e32 v2, v51, v2
	v_add_f32_e32 v2, v51, v2
	v_cvt_pk_bf16_f32 v10, v56, v57
	v_cvt_pk_bf16_f32 v11, v62, v11
	s_waitcnt lgkmcnt(0)
	v_mfma_f32_32x32x16_bf16 v[34:49], v[14:17], v[6:9], v[34:49]
	v_cvt_pk_bf16_f32 v12, v51, v51
	v_cvt_pk_bf16_f32 v13, v51, v51
	v_add_f32_e32 v6, v51, v2
	ds_read2_b64 v[2:5], v71 offset0:32 offset1:34
	ds_read2_b64 v[14:17], v68 offset0:32 offset1:34
	v_add_f32_e32 v6, v51, v6
	v_add_f32_e32 v54, v51, v6
	s_waitcnt lgkmcnt(1)
	v_mfma_f32_32x32x16_bf16 v[18:33], v[2:5], v[10:13], v[18:33]
	v_add_f32_e32 v2, v51, v54
	v_sub_f32_e32 v0, v85, v0
	v_mul_f32_e32 v0, 0x3fb8aa3b, v0
	v_exp_f32_e32 v0, v0
	v_cvt_pk_bf16_f32 v6, v51, v51
	v_cvt_pk_bf16_f32 v7, v51, v51
	v_cvt_pk_bf16_f32 v8, v51, v51
	s_waitcnt lgkmcnt(0)
	v_mfma_f32_32x32x16_bf16 v[34:49], v[14:17], v[10:13], v[34:49]
	v_add_f32_e32 v10, v51, v2
	ds_bpermute_b32 v11, v152, v10
	v_cvt_pk_bf16_f32 v9, v51, v51
	ds_read2_b64 v[14:17], v68 offset0:36 offset1:38
	ds_read2_b64 v[2:5], v71 offset0:36 offset1:38
	v_mov_b32_e32 v51, v1
	s_waitcnt lgkmcnt(2)
	v_add_f32_e32 v10, v10, v11
	v_add_f32_e32 v0, v0, v10
	v_div_scale_f32 v12, s[0:1], v0, v0, 1.0
	v_rcp_f32_e32 v13, v12
	s_waitcnt lgkmcnt(1)
	v_mfma_f32_32x32x16_bf16 v[34:49], v[14:17], v[6:9], v[34:49]
	v_readlane_b32 s0, v253, 43
	v_readlane_b32 s1, v253, 44
	s_nop 1
	v_lshl_add_u64 v[10:11], s[0:1], 0, v[52:53]
	v_lshl_add_u64 v[10:11], v[10:11], 0, v[82:83]
	s_waitcnt lgkmcnt(0)
	v_mfma_f32_32x32x16_bf16 v[18:33], v[2:5], v[6:9], v[18:33]
	v_fma_f32 v2, -v12, v13, 1.0
	v_fmac_f32_e32 v13, v2, v13
	v_div_scale_f32 v2, vcc, 1.0, v0, 1.0
	v_mul_f32_e32 v3, v2, v13
	v_fma_f32 v4, -v12, v3, v2
	v_fmac_f32_e32 v3, v4, v13
	v_fma_f32 v2, -v12, v3, v2
	v_div_fmas_f32 v2, v2, v13, v3
	v_div_fixup_f32 v0, v2, v0, 1.0
	v_mul_f32_e32 v4, v34, v0
	v_mul_f32_e32 v5, v35, v0
	v_cvt_pk_bf16_f32 v4, v4, v5
	v_mul_f32_e32 v5, v36, v0
	v_lshl_add_u64 v[2:3], v[10:11], 0, v[50:51]
	v_mul_f32_e32 v6, v37, v0
	v_cvt_pk_bf16_f32 v5, v5, v6
	global_store_dwordx2 v[2:3], v[4:5], off
	v_mul_f32_e32 v4, v38, v0
	v_mul_f32_e32 v5, v39, v0
	v_cvt_pk_bf16_f32 v4, v4, v5
	v_mul_f32_e32 v5, v40, v0
	v_mul_f32_e32 v6, v41, v0
	v_cvt_pk_bf16_f32 v5, v5, v6
	global_store_dwordx2 v[2:3], v[4:5], off offset:16
	v_mul_f32_e32 v4, v42, v0
	v_mul_f32_e32 v5, v43, v0
	v_cvt_pk_bf16_f32 v4, v4, v5
	v_mul_f32_e32 v5, v44, v0
	v_mul_f32_e32 v6, v45, v0
	v_cvt_pk_bf16_f32 v5, v5, v6
	global_store_dwordx2 v[2:3], v[4:5], off offset:32
	v_mul_f32_e32 v4, v46, v0
	v_mul_f32_e32 v5, v47, v0
	v_cvt_pk_bf16_f32 v4, v4, v5
	v_mul_f32_e32 v5, v48, v0
	v_mul_f32_e32 v6, v49, v0
	v_cvt_pk_bf16_f32 v5, v5, v6
	global_store_dwordx2 v[2:3], v[4:5], off offset:48
	v_mul_f32_e32 v4, v18, v0
	v_mul_f32_e32 v5, v19, v0
	v_cvt_pk_bf16_f32 v4, v4, v5
	v_mul_f32_e32 v5, v20, v0
	v_mul_f32_e32 v6, v21, v0
	v_cvt_pk_bf16_f32 v5, v5, v6
	global_store_dwordx2 v[2:3], v[4:5], off offset:64
	v_mul_f32_e32 v4, v22, v0
	v_mul_f32_e32 v5, v23, v0
	v_cvt_pk_bf16_f32 v4, v4, v5
	v_mul_f32_e32 v5, v24, v0
	v_mul_f32_e32 v6, v25, v0
	v_cvt_pk_bf16_f32 v5, v5, v6
	global_store_dwordx2 v[2:3], v[4:5], off offset:80
	v_mul_f32_e32 v4, v26, v0
	v_mul_f32_e32 v5, v27, v0
	v_cvt_pk_bf16_f32 v4, v4, v5
	v_mul_f32_e32 v5, v28, v0
	v_mul_f32_e32 v6, v29, v0
	v_cvt_pk_bf16_f32 v5, v5, v6
	global_store_dwordx2 v[2:3], v[4:5], off offset:96
	v_mul_f32_e32 v4, v30, v0
	v_mul_f32_e32 v5, v31, v0
	v_cvt_pk_bf16_f32 v4, v4, v5
	v_mul_f32_e32 v5, v32, v0
	v_mul_f32_e32 v0, v33, v0
	v_cvt_pk_bf16_f32 v5, v5, v0
	global_store_dwordx2 v[2:3], v[4:5], off offset:112
